# adds on v90: fp8 K-loop DMA base setup (2 v_readfirstlane + bias subtract) hoisted in front of the loop - no VALU at the iteration head right after the barrier release
# speedup vs baseline: 1.0002x; 1.0002x over previous
; __device__ __forceinline__ int lane_id_hw() { int l; asm volatile("v_mbcnt_lo_u32_b32 %0, -1, 0\n\tv_mbcnt_hi_u32_b32 %0, -1, %0" : "=v"(l)); return l; }
; #define PG8_STAGE(bufoff, gbase, voff) do { unsigned _g = (gbase); asm volatile("" : "+s"(_g));   _Pragma("unroll") for (int _i = 0; _i < 2; ++_i) \
;         __builtin_amdgcn_global_load_lds((const unsigned*)(wsb + (size_t)(unsigned)(_g + (voff)[_i])), (LAS unsigned*)(lds + (bufoff) + ldsw + _i * 8192), 16, 0, 0); } while (0)
; #define PG8_WAIT_V(n) asm volatile("s_waitcnt vmcnt(" #n ")" ::: "memory")
; #define PG8_WAIT_L(n) asm volatile("s_waitcnt lgkmcnt(" #n ")" ::: "memory")
; #define PG8_BAR __builtin_amdgcn_s_barrier()
; #define PG8_SCHED __builtin_amdgcn_sched_barrier(0)
;     ...
;         const bool has_next = S.next(ui + 1, nxt);
;         const unsigned nA = has_next ? nxt.ao : cA, nB = has_next ? nxt.bo : cB;
;         const int nt = cur.nt;
;         for (int t = 0; t < nt; t += 2) {
;             if constexpr (Epi::HAS_MID) { if (t == Epi::MID0 || t == Epi::MID1) { const int l2 = lane_id_hw(); E.mid(acc, cur, t == Epi::MID0 ? 0 : 1, wr, wc, l2 & 15, l2 >> 4); } }
;             const bool last = (t == nt - 2);
;             const unsigned a1 = cA + (unsigned)(t + 1) * kstep;
;             const unsigned a2 = last ? nA : cA + (unsigned)(t + 2) * kstep, b2 = last ? nB : cB + (unsigned)(t + 2) * kstep;
;             const unsigned a3 = a2 + kstep, b3 = b2 + kstep;
;             if constexpr (SP2) {
;             PG8_LDB(B0, 0, 0); PG8_LDB(B1, 0, 1); PG8_SCHED; PG8_LDA(At, 0, 0); PG8_STAGE(PG8_SA(1, 1), a1 + hstep, voffA);
;             PG8_WAIT_V(8); PG8_WAIT_L(0); PG8_BAR; PG8_MMA(0, 0, At, B0); PG8_MMA(0, 1, At, B1); PG8_BAR; PG8_SCHED;
;     ...
;         for (int a = 0; a < 2; ++a)
; #pragma unroll
;             for (int b = 0; b < 2; ++b)
; #pragma unroll
;                 for (int m = 0; m < 4; ++m)
; #pragma unroll
;                     for (int n = 0; n < 2; ++n) acc[a][b][m][n] = (f32x4){0.f, 0.f, 0.f, 0.f};
.LBB0_558:
	v_mov_b32_e32 v2, 0
	s_add_i32 s44, s44, 0x80080
	s_addk_i32 s45, 0x100
	s_mov_b32 s46, -2
	v_mov_b32_e32 v3, v2
	v_mov_b32_e32 v4, v2
	v_mov_b32_e32 v5, v2
	v_mov_b32_e32 v6, v2
	v_mov_b32_e32 v7, v2
	v_mov_b32_e32 v8, v2
	v_mov_b32_e32 v9, v2
	v_mov_b32_e32 v18, v2
	v_mov_b32_e32 v19, v2
	v_mov_b32_e32 v20, v2
	v_mov_b32_e32 v21, v2
	v_mov_b32_e32 v22, v2
	v_mov_b32_e32 v23, v2
	v_mov_b32_e32 v24, v2
	v_mov_b32_e32 v25, v2
	v_mov_b32_e32 v34, v2
	v_mov_b32_e32 v35, v2
	v_mov_b32_e32 v36, v2
	v_mov_b32_e32 v37, v2
	v_mov_b32_e32 v38, v2
	v_mov_b32_e32 v39, v2
	v_mov_b32_e32 v40, v2
	v_mov_b32_e32 v41, v2
	v_mov_b32_e32 v50, v2
	v_mov_b32_e32 v51, v2
	v_mov_b32_e32 v52, v2
	v_mov_b32_e32 v53, v2
	v_mov_b32_e32 v54, v2
	v_mov_b32_e32 v55, v2
	v_mov_b32_e32 v56, v2
	v_mov_b32_e32 v57, v2
	v_mov_b32_e32 v10, v2
	v_mov_b32_e32 v11, v2
	v_mov_b32_e32 v12, v2
	v_mov_b32_e32 v13, v2
	v_mov_b32_e32 v14, v2
	v_mov_b32_e32 v15, v2
	v_mov_b32_e32 v16, v2
	v_mov_b32_e32 v17, v2
	v_mov_b32_e32 v26, v2
	v_mov_b32_e32 v27, v2
	v_mov_b32_e32 v28, v2
	v_mov_b32_e32 v29, v2
	v_mov_b32_e32 v30, v2
	v_mov_b32_e32 v31, v2
	v_mov_b32_e32 v32, v2
	v_mov_b32_e32 v33, v2
	v_mov_b32_e32 v42, v2
	v_mov_b32_e32 v43, v2
	v_mov_b32_e32 v44, v2
	v_mov_b32_e32 v45, v2
	v_mov_b32_e32 v46, v2
	v_mov_b32_e32 v47, v2
	v_mov_b32_e32 v48, v2
	v_mov_b32_e32 v49, v2
	v_mov_b32_e32 v58, v2
	v_mov_b32_e32 v59, v2
	v_mov_b32_e32 v60, v2
	v_mov_b32_e32 v61, v2
	v_mov_b32_e32 v62, v2
	v_mov_b32_e32 v63, v2
	v_mov_b32_e32 v64, v2
	v_mov_b32_e32 v65, v2
	v_mov_b32_e32 v66, v2
	v_mov_b32_e32 v67, v2
	v_mov_b32_e32 v68, v2
	v_mov_b32_e32 v69, v2
	v_mov_b32_e32 v70, v2
	v_mov_b32_e32 v71, v2
	v_mov_b32_e32 v72, v2
	v_mov_b32_e32 v73, v2
	v_mov_b32_e32 v82, v2
	v_mov_b32_e32 v83, v2
	v_mov_b32_e32 v84, v2
	v_mov_b32_e32 v85, v2
	v_mov_b32_e32 v86, v2
	v_mov_b32_e32 v87, v2
	v_mov_b32_e32 v88, v2
	v_mov_b32_e32 v89, v2
	v_mov_b32_e32 v98, v2
	v_mov_b32_e32 v99, v2
	v_mov_b32_e32 v100, v2
	v_mov_b32_e32 v101, v2
	v_mov_b32_e32 v102, v2
	v_mov_b32_e32 v103, v2
	v_mov_b32_e32 v104, v2
	v_mov_b32_e32 v105, v2
	v_mov_b32_e32 v114, v2
	v_mov_b32_e32 v115, v2
	v_mov_b32_e32 v116, v2
	v_mov_b32_e32 v117, v2
	v_mov_b32_e32 v118, v2
	v_mov_b32_e32 v119, v2
	v_mov_b32_e32 v120, v2
	v_mov_b32_e32 v121, v2
	v_mov_b32_e32 v74, v2
	v_mov_b32_e32 v75, v2
	v_mov_b32_e32 v76, v2
	v_mov_b32_e32 v77, v2
	v_mov_b32_e32 v78, v2
	v_mov_b32_e32 v79, v2
	v_mov_b32_e32 v80, v2
	v_mov_b32_e32 v81, v2
	v_mov_b32_e32 v90, v2
	v_mov_b32_e32 v91, v2
	v_mov_b32_e32 v92, v2
	v_mov_b32_e32 v93, v2
	v_mov_b32_e32 v94, v2
	v_mov_b32_e32 v95, v2
	v_mov_b32_e32 v96, v2
	v_mov_b32_e32 v97, v2
	v_mov_b32_e32 v106, v2
	v_mov_b32_e32 v107, v2
	v_mov_b32_e32 v108, v2
	v_mov_b32_e32 v109, v2
	v_mov_b32_e32 v110, v2
	v_mov_b32_e32 v111, v2
	v_mov_b32_e32 v112, v2
	v_mov_b32_e32 v113, v2
	v_mov_b32_e32 v122, v2
	v_mov_b32_e32 v123, v2
	v_mov_b32_e32 v124, v2
	v_mov_b32_e32 v125, v2
	v_mov_b32_e32 v126, v2
	v_mov_b32_e32 v127, v2
	v_mov_b32_e32 v128, v2
	v_mov_b32_e32 v129, v2
	v_readlane_b32 s98, v255, 4
	s_nop 3
	s_cmp_lg_u32 s98, 0
	s_cbranch_scc0 .Lprio_skip_1
	s_setprio 1
.Lprio_skip_1:
	v_readfirstlane_b32 s100, v130
	v_readfirstlane_b32 s101, v131
	s_nop 1
	s_sub_u32 s100, s100, 0x10000000
	s_subb_u32 s101, s101, 0
.LBB0_559:
	s_add_i32 s47, s44, 0xfff80080
	s_cmp_eq_u32 s46, 28
	s_cselect_b32 s83, s36, s47
	s_cselect_b32 s47, s37, s45
	s_add_i32 s84, 0, 0x10000
	v_add_u32_e32 v0, s84, v138
	s_add_i32 s86, 0, 0x14000
	ds_read_b128 v[140:143], v0
	ds_read_b128 v[144:147], v0 offset:1024
	ds_read_b128 v[148:151], v0 offset:2048
	ds_read_b128 v[152:155], v0 offset:3072
	v_add_u32_e32 v0, s86, v138
	ds_read_b128 v[156:159], v0
	ds_read_b128 v[160:163], v0 offset:1024
	ds_read_b128 v[164:167], v0 offset:2048
	ds_read_b128 v[168:171], v0 offset:3072
	s_add_i32 s82, s83, 0x80
	s_mov_b32 s87, s44
	ds_read_b128 v[172:175], v139
	ds_read_b128 v[176:179], v139 offset:1024
	ds_read_b128 v[180:183], v139 offset:2048
	ds_read_b128 v[184:187], v139 offset:3072
	ds_read_b128 v[188:191], v139 offset:4096
	ds_read_b128 v[192:195], v139 offset:5120
	ds_read_b128 v[196:199], v139 offset:6144
	ds_read_b128 v[200:203], v139 offset:7168
	s_add_i32 m0, s9, 0xc000
	s_add_i32 vcc_lo, s87, 0x10000000
	s_add_u32 vcc_lo, s100, vcc_lo
	s_addc_u32 vcc_hi, s101, 0
	global_load_lds_dwordx4 v134, vcc
	s_add_i32 m0, s9, 0xe000
	s_nop 0
	global_load_lds_dwordx4 v136, vcc
	s_waitcnt vmcnt(8)
	s_waitcnt lgkmcnt(0)
	s_barrier
	s_waitcnt lgkmcnt(0)
	v_mfma_f32_16x16x128_f8f6f4 v[126:129], v[140:147], v[172:179], v[126:129]
	v_mfma_f32_16x16x128_f8f6f4 v[122:125], v[148:155], v[172:179], v[122:125]
	v_mfma_f32_16x16x128_f8f6f4 v[110:113], v[140:147], v[180:187], v[110:113]
	v_mfma_f32_16x16x128_f8f6f4 v[106:109], v[148:155], v[180:187], v[106:109]
	v_mfma_f32_16x16x128_f8f6f4 v[204:207], v[140:147], v[188:195], v[94:97]
	v_mfma_f32_16x16x128_f8f6f4 v[208:211], v[148:155], v[188:195], v[90:93]
	v_mfma_f32_16x16x128_f8f6f4 v[212:215], v[140:147], v[196:203], v[78:81]
	v_mfma_f32_16x16x128_f8f6f4 v[216:219], v[148:155], v[196:203], v[74:77]
	v_mfma_f32_16x16x128_f8f6f4 v[118:121], v[156:163], v[172:179], v[118:121]
	v_mfma_f32_16x16x128_f8f6f4 v[114:117], v[164:171], v[172:179], v[114:117]
	v_mfma_f32_16x16x128_f8f6f4 v[102:105], v[156:163], v[180:187], v[102:105]
	v_mfma_f32_16x16x128_f8f6f4 v[98:101], v[164:171], v[180:187], v[98:101]
	v_mfma_f32_16x16x128_f8f6f4 v[172:175], v[156:163], v[188:195], v[86:89]
	v_mfma_f32_16x16x128_f8f6f4 v[176:179], v[164:171], v[188:195], v[82:85]
	v_mfma_f32_16x16x128_f8f6f4 v[180:183], v[156:163], v[196:203], v[70:73]
	v_mfma_f32_16x16x128_f8f6f4 v[184:187], v[164:171], v[196:203], v[66:69]
	s_barrier
; #define PG8_STAGE(bufoff, gbase, voff) do { unsigned _g = (gbase); asm volatile("" : "+s"(_g));   _Pragma("unroll") for (int _i = 0; _i < 2; ++_i) \
;         __builtin_amdgcn_global_load_lds((const unsigned*)(wsb + (size_t)(unsigned)(_g + (voff)[_i])), (LAS unsigned*)(lds + (bufoff) + ldsw + _i * 8192), 16, 0, 0); } while (0)
; #define PG8_WAIT_V(n) asm volatile("s_waitcnt vmcnt(" #n ")" ::: "memory")
; #define PG8_WAIT_L(n) asm volatile("s_waitcnt lgkmcnt(" #n ")" ::: "memory")
; #define PG8_BAR __builtin_amdgcn_s_barrier()
; #define PG8_SCHED __builtin_amdgcn_sched_barrier(0)
;     ...
;             PG8_WAIT_V(8); PG8_WAIT_L(0); PG8_BAR; PG8_MMA(0, 0, At, B0); PG8_MMA(0, 1, At, B1); PG8_BAR; PG8_SCHED;
;             PG8_LDA(At, 0, 1); PG8_STAGE(PG8_SB(0, 0), b2, voffB); PG8_STAGE(PG8_SB(0, 1), b2 + hstep, voffB); PG8_STAGE(PG8_SA(0, 0), a2, voffA);
;             PG8_WAIT_V(8); PG8_WAIT_L(0); PG8_BAR; PG8_MMA(1, 0, At, B0); PG8_MMA(1, 1, At, B1); PG8_BAR; PG8_SCHED;
;             PG8_LDB(B0, 1, 0); PG8_LDB(B1, 1, 1); PG8_SCHED; PG8_LDA(At, 1, 0); PG8_STAGE(PG8_SA(0, 1), a2 + hstep, voffA);
;             PG8_WAIT_V(8); PG8_WAIT_L(0); PG8_BAR; PG8_MMA(0, 0, At, B0); PG8_MMA(0, 1, At, B1); PG8_BAR; PG8_SCHED;
;             PG8_LDA(At, 1, 1); PG8_STAGE(PG8_SB(1, 0), b3, voffB); PG8_STAGE(PG8_SB(1, 1), b3 + hstep, voffB); PG8_STAGE(PG8_SA(1, 0), a3, voffA);
	s_mov_b32 s87, s47
	s_nop 3
	ds_read_b128 v[66:69], v139 offset:16384
	ds_read_b128 v[70:73], v139 offset:17408
	ds_read_b128 v[74:77], v139 offset:18432
	ds_read_b128 v[78:81], v139 offset:19456
	ds_read_b128 v[82:85], v139 offset:20480
	ds_read_b128 v[86:89], v139 offset:21504
	ds_read_b128 v[90:93], v139 offset:22528
	ds_read_b128 v[94:97], v139 offset:23552
	s_add_i32 s84, s84, s7
	s_add_i32 vcc_lo, s87, 0x10000000
	s_add_u32 vcc_lo, s100, vcc_lo
	s_addc_u32 vcc_hi, s101, 0
	s_mov_b32 m0, s84
	s_nop 0
	global_load_lds_dwordx4 v135, vcc
	s_add_i32 m0, s84, 0x2000
	s_add_i32 s84, s47, 0x80000
	global_load_lds_dwordx4 v137, vcc
	s_add_i32 s86, s86, s7
	s_add_i32 vcc_lo, s84, 0x10000000
	s_add_u32 vcc_lo, s100, vcc_lo
	s_addc_u32 vcc_hi, s101, 0
	s_mov_b32 m0, s86
	s_nop 0
	global_load_lds_dwordx4 v135, vcc
	s_add_i32 m0, s86, 0x2000
	s_mov_b32 s84, s83
	global_load_lds_dwordx4 v137, vcc
	s_mov_b32 m0, s9
	s_add_i32 vcc_lo, s84, 0x10000000
	s_add_u32 vcc_lo, s100, vcc_lo
	s_addc_u32 vcc_hi, s101, 0
	global_load_lds_dwordx4 v134, vcc
	s_mov_b32 m0, s11
	s_nop 0
	global_load_lds_dwordx4 v136, vcc
	s_waitcnt vmcnt(8)
	s_waitcnt lgkmcnt(0)
	s_barrier
	s_waitcnt lgkmcnt(0)
	v_mfma_f32_16x16x128_f8f6f4 v[62:65], v[140:147], v[66:73], v[62:65]
	v_mfma_f32_16x16x128_f8f6f4 v[58:61], v[148:155], v[66:73], v[58:61]
	v_mfma_f32_16x16x128_f8f6f4 v[188:191], v[140:147], v[74:81], v[46:49]
	v_mfma_f32_16x16x128_f8f6f4 v[192:195], v[148:155], v[74:81], v[42:45]
	v_mfma_f32_16x16x128_f8f6f4 v[196:199], v[140:147], v[82:89], v[30:33]
	v_mfma_f32_16x16x128_f8f6f4 v[200:203], v[148:155], v[82:89], v[26:29]
	v_mfma_f32_16x16x128_f8f6f4 v[220:223], v[140:147], v[90:97], v[14:17]
	v_mfma_f32_16x16x128_f8f6f4 v[224:227], v[148:155], v[90:97], v[10:13]
	v_mfma_f32_16x16x128_f8f6f4 v[54:57], v[156:163], v[66:73], v[54:57]
	v_mfma_f32_16x16x128_f8f6f4 v[50:53], v[164:171], v[66:73], v[50:53]
	v_mfma_f32_16x16x128_f8f6f4 v[228:231], v[156:163], v[74:81], v[38:41]
	v_mfma_f32_16x16x128_f8f6f4 v[232:235], v[164:171], v[74:81], v[34:37]
	v_mfma_f32_16x16x128_f8f6f4 v[236:239], v[156:163], v[82:89], v[22:25]
	v_mfma_f32_16x16x128_f8f6f4 v[246:249], v[164:171], v[82:89], v[18:21]
	v_mfma_f32_16x16x128_f8f6f4 v[250:253], v[156:163], v[90:97], v[6:9]
	v_mfma_f32_16x16x128_f8f6f4 v[240:243], v[164:171], v[90:97], v[2:5]
	s_barrier
	s_add_i32 s84, 0, 0x18000
	v_add_u32_e32 v0, s84, v138
	s_add_i32 s86, 0, 0x1c000
	s_nop 1
	ds_read_b128 v[2:5], v0
	ds_read_b128 v[6:9], v0 offset:1024
	ds_read_b128 v[18:21], v0 offset:2048
	ds_read_b128 v[22:25], v0 offset:3072
	v_add_u32_e32 v0, s86, v138
	ds_read_b128 v[140:143], v0
	ds_read_b128 v[144:147], v0 offset:1024
	ds_read_b128 v[148:151], v0 offset:2048
	ds_read_b128 v[152:155], v0 offset:3072
	s_add_i32 s83, s83, 0x80000
	ds_read_b128 v[10:13], v139 offset:32768
	ds_read_b128 v[14:17], v139 offset:33792
	ds_read_b128 v[26:29], v139 offset:34816
	ds_read_b128 v[30:33], v139 offset:35840
	ds_read_b128 v[34:37], v139 offset:36864
	ds_read_b128 v[38:41], v139 offset:37888
	ds_read_b128 v[42:45], v139 offset:38912
	ds_read_b128 v[46:49], v139 offset:39936
	s_mov_b32 m0, s12
	s_add_i32 vcc_lo, s83, 0x10000000
	s_add_u32 vcc_lo, s100, vcc_lo
	s_addc_u32 vcc_hi, s101, 0
	global_load_lds_dwordx4 v134, vcc
	s_mov_b32 m0, s13
	s_nop 0
	global_load_lds_dwordx4 v136, vcc
	s_waitcnt vmcnt(8)
	s_waitcnt lgkmcnt(0)
	s_barrier
	s_waitcnt lgkmcnt(0)
	v_mfma_f32_16x16x128_f8f6f4 v[126:129], v[2:9], v[10:17], v[126:129]
	v_mfma_f32_16x16x128_f8f6f4 v[122:125], v[18:25], v[10:17], v[122:125]
	v_mfma_f32_16x16x128_f8f6f4 v[110:113], v[2:9], v[26:33], v[110:113]
	v_mfma_f32_16x16x128_f8f6f4 v[106:109], v[18:25], v[26:33], v[106:109]
	v_mfma_f32_16x16x128_f8f6f4 v[94:97], v[2:9], v[34:41], v[204:207]
	v_mfma_f32_16x16x128_f8f6f4 v[90:93], v[18:25], v[34:41], v[208:211]
	v_mfma_f32_16x16x128_f8f6f4 v[78:81], v[2:9], v[42:49], v[212:215]
	v_mfma_f32_16x16x128_f8f6f4 v[74:77], v[18:25], v[42:49], v[216:219]
	v_mfma_f32_16x16x128_f8f6f4 v[118:121], v[140:147], v[10:17], v[118:121]
	v_mfma_f32_16x16x128_f8f6f4 v[114:117], v[148:155], v[10:17], v[114:117]
	v_mfma_f32_16x16x128_f8f6f4 v[102:105], v[140:147], v[26:33], v[102:105]
	v_mfma_f32_16x16x128_f8f6f4 v[98:101], v[148:155], v[26:33], v[98:101]
	v_mfma_f32_16x16x128_f8f6f4 v[86:89], v[140:147], v[34:41], v[172:175]
	v_mfma_f32_16x16x128_f8f6f4 v[82:85], v[148:155], v[34:41], v[176:179]
	v_mfma_f32_16x16x128_f8f6f4 v[70:73], v[140:147], v[42:49], v[180:183]
	v_mfma_f32_16x16x128_f8f6f4 v[66:69], v[148:155], v[42:49], v[184:187]
	s_barrier
	s_add_i32 s83, s47, 0x80
	ds_read_b128 v[34:37], v139 offset:49152
	ds_read_b128 v[38:41], v139 offset:50176
	ds_read_b128 v[156:159], v139 offset:51200
	ds_read_b128 v[160:163], v139 offset:52224
	ds_read_b128 v[164:167], v139 offset:53248
	ds_read_b128 v[168:171], v139 offset:54272
	ds_read_b128 v[172:175], v139 offset:55296
	ds_read_b128 v[176:179], v139 offset:56320
	s_add_i32 s84, s84, s7
	s_add_i32 vcc_lo, s83, 0x10000000
	s_add_u32 vcc_lo, s100, vcc_lo
	s_addc_u32 vcc_hi, s101, 0
	s_mov_b32 m0, s84
	s_nop 0
	global_load_lds_dwordx4 v135, vcc
	s_add_i32 m0, s84, 0x2000
	s_add_i32 s47, s47, 0x80080
	global_load_lds_dwordx4 v137, vcc
	s_add_i32 s83, s86, s7
	s_add_i32 vcc_lo, s47, 0x10000000
	s_add_u32 vcc_lo, s100, vcc_lo
	s_addc_u32 vcc_hi, s101, 0
	s_mov_b32 m0, s83
	s_nop 0
	global_load_lds_dwordx4 v135, vcc
	s_add_i32 m0, s83, 0x2000
	s_nop 0
	global_load_lds_dwordx4 v137, vcc
	s_mov_b32 m0, s18
	s_add_i32 vcc_lo, s82, 0x10000000
	s_add_u32 vcc_lo, s100, vcc_lo
	s_addc_u32 vcc_hi, s101, 0
	global_load_lds_dwordx4 v134, vcc
	s_mov_b32 m0, s22
	s_nop 0
	global_load_lds_dwordx4 v136, vcc
	s_waitcnt vmcnt(8)
	s_waitcnt lgkmcnt(0)
	s_barrier
; #define GAS __attribute__((address_space(1)))
; __device__ __forceinline__ unsigned gate_pk4(const f32x4& g) { return gate_q8(g[0]) | (gate_q8(g[1]) << 8) | (gate_q8(g[2]) << 16) | (gate_q8(g[3]) << 24); }
; #define PG8_WAIT_V(n) asm volatile("s_waitcnt vmcnt(" #n ")" ::: "memory")
; #define PG8_WAIT_L(n) asm volatile("s_waitcnt lgkmcnt(" #n ")" ::: "memory")
; #define PG8_BAR __builtin_amdgcn_s_barrier()
; #define PG8_SCHED __builtin_amdgcn_sched_barrier(0)
;     ...
;             PG8_WAIT_V(8); PG8_WAIT_L(0); PG8_BAR; PG8_MMA(1, 0, At, B0); PG8_MMA(1, 1, At, B1); PG8_BAR; PG8_SCHED;
;     __device__ __forceinline__ void operator()(const f32x4 (&acc)[2][2][4][2], const pg8::GUnit& u, int wr, int wc, int fr, int fq) const {
;     ...
;         GAS unsigned char* gb = (GAS unsigned char*)P + (size_t)(u.pm * 256 + (wr * 4 + wc) * 32 + fq) * (INW * 2) + (GA * 2 + u.pn * 256 + fr * 16);
; #pragma unroll
;         for (int ai = 0; ai < 2; ++ai)
; #pragma unroll
;             for (int m = 0; m < 4; ++m) { u32x4 w; unsigned wq[4];
; #pragma unroll
;                 for (int bj = 0; bj < 2; ++bj)
; #pragma unroll
;                     for (int n = 0; n < 2; ++n) { f32x4 v = acc[ai][bj][m][n];
; #pragma unroll
;                         for (int j = 0; j < 4; ++j) v[j] = __builtin_amdgcn_rcpf(1.0f + __builtin_amdgcn_exp2f(v[j] * (-LOG2E * G8_DESCALE)));
;                         wq[bj * 2 + n] = gate_pk4(v); }
;                 w.x = wq[0]; w.y = wq[1]; w.z = wq[2]; w.w = wq[3];
;                 *(GAS u32x4*)(gb + (size_t)((ai * 4 + m) * 4) * (INW * 2)) = w; }
	s_waitcnt lgkmcnt(0)
	v_mfma_f32_16x16x128_f8f6f4 v[62:65], v[2:9], v[34:41], v[62:65]
	v_mfma_f32_16x16x128_f8f6f4 v[58:61], v[18:25], v[34:41], v[58:61]
	v_mfma_f32_16x16x128_f8f6f4 v[46:49], v[2:9], v[156:163], v[188:191]
	v_mfma_f32_16x16x128_f8f6f4 v[42:45], v[18:25], v[156:163], v[192:195]
	v_mfma_f32_16x16x128_f8f6f4 v[30:33], v[2:9], v[164:171], v[196:199]
	v_mfma_f32_16x16x128_f8f6f4 v[26:29], v[18:25], v[164:171], v[200:203]
	v_mfma_f32_16x16x128_f8f6f4 v[14:17], v[2:9], v[172:179], v[220:223]
	v_mfma_f32_16x16x128_f8f6f4 v[10:13], v[18:25], v[172:179], v[224:227]
	v_mfma_f32_16x16x128_f8f6f4 v[54:57], v[140:147], v[34:41], v[54:57]
	v_mfma_f32_16x16x128_f8f6f4 v[50:53], v[148:155], v[34:41], v[50:53]
	v_mfma_f32_16x16x128_f8f6f4 v[38:41], v[140:147], v[156:163], v[228:231]
	v_mfma_f32_16x16x128_f8f6f4 v[34:37], v[148:155], v[156:163], v[232:235]
	v_mfma_f32_16x16x128_f8f6f4 v[22:25], v[140:147], v[164:171], v[236:239]
	v_mfma_f32_16x16x128_f8f6f4 v[18:21], v[148:155], v[164:171], v[246:249]
	v_mfma_f32_16x16x128_f8f6f4 v[6:9], v[140:147], v[172:179], v[250:253]
	v_mfma_f32_16x16x128_f8f6f4 v[2:5], v[148:155], v[172:179], v[240:243]
	s_barrier
	s_add_i32 s46, s46, 2
	s_addk_i32 s44, 0x100
	s_addk_i32 s45, 0x100
	s_cmp_gt_u32 s46, 29
	s_cbranch_scc0 .LBB0_559
	s_setprio 0
	v_mbcnt_lo_u32_b32 v0, -1, 0
	v_mbcnt_hi_u32_b32 v0, -1, v0
	s_lshl_b32 s38, s38, 8
	v_ashrrev_i32_e32 v140, 4, v0
	v_lshlrev_b32_e32 v0, 4, v0
	s_addk_i32 s38, 0x6000
	v_and_b32_e32 v0, 0xf0, v0
	v_or_b32_e32 v142, s38, v0
	v_mul_f32_e32 v0, 0xba38aa3b, v126
	v_mul_f32_e32 v126, 0xba38aa3b, v127
	v_exp_f32_e32 v126, v126
	v_mul_f32_e32 v127, 0xba38aa3b, v128
	v_exp_f32_e32 v127, v127
	v_exp_f32_e32 v0, v0
	v_mul_f32_e32 v128, 0xba38aa3b, v129
	v_add_f32_e32 v126, 1.0, v126
	v_exp_f32_e32 v128, v128
	v_rcp_f32_e32 v126, v126
	v_add_f32_e32 v127, 1.0, v127
	v_add_f32_e32 v0, 1.0, v0
	v_rcp_f32_e32 v127, v127
	v_rcp_f32_e32 v0, v0
	v_add_f32_e32 v128, 1.0, v128
	v_rcp_f32_e32 v128, v128
	v_fma_f32 v126, v126, s49, 0.5
	v_max_f32_e32 v126, 1.0, v126
	v_cvt_u32_f32_e32 v129, v126
	v_fma_f32 v126, v127, s49, 0.5
	v_fma_f32 v0, v0, s49, 0.5
	v_max_f32_e32 v126, 1.0, v126
	v_max_f32_e32 v0, 1.0, v0
	v_cvt_u32_f32_sdwa v144, v126 dst_sel:WORD_1 dst_unused:UNUSED_PAD src0_sel:DWORD
	v_fma_f32 v126, v128, s49, 0.5
	v_cvt_u32_f32_e32 v0, v0
	v_max_f32_e32 v126, 1.0, v126
	v_mul_f32_e32 v122, 0xba38aa3b, v122
	v_mul_f32_e32 v123, 0xba38aa3b, v123
	v_cvt_u32_f32_sdwa v128, v126 dst_sel:BYTE_3 dst_unused:UNUSED_PAD src0_sel:DWORD
	v_exp_f32_e32 v145, v122
	v_exp_f32_e32 v123, v123
	v_lshl_or_b32 v0, v129, 8, v0
	v_or3_b32 v122, v0, v144, v128
	v_add_f32_e32 v0, 1.0, v145
	v_add_f32_e32 v123, 1.0, v123
	v_mul_f32_e32 v124, 0xba38aa3b, v124
	v_rcp_f32_e32 v0, v0
	v_rcp_f32_e32 v123, v123
	v_mul_f32_e32 v125, 0xba38aa3b, v125
	v_mul_f32_e32 v118, 0xba38aa3b, v118
	v_mul_f32_e32 v119, 0xba38aa3b, v119
	v_exp_f32_e32 v124, v124
	v_exp_f32_e32 v125, v125
	v_exp_f32_e32 v118, v118
	v_exp_f32_e32 v119, v119
	v_mul_f32_e32 v120, 0xba38aa3b, v120
	v_mul_f32_e32 v121, 0xba38aa3b, v121
	v_exp_f32_e32 v120, v120
	v_exp_f32_e32 v121, v121
	v_fma_f32 v0, v0, s49, 0.5
	v_fma_f32 v123, v123, s49, 0.5
	v_add_f32_e32 v124, 1.0, v124
	v_max_f32_e32 v0, 1.0, v0
	v_max_f32_e32 v123, 1.0, v123
	v_add_f32_e32 v125, 1.0, v125
	v_add_f32_e32 v118, 1.0, v118
	v_add_f32_e32 v119, 1.0, v119
	v_cvt_u32_f32_e32 v0, v0
	v_cvt_u32_f32_e32 v123, v123
	v_rcp_f32_e32 v124, v124
	v_rcp_f32_e32 v125, v125
	v_rcp_f32_e32 v118, v118
	v_rcp_f32_e32 v119, v119
	v_add_f32_e32 v120, 1.0, v120
	v_add_f32_e32 v121, 1.0, v121
	v_rcp_f32_e32 v120, v120
	v_rcp_f32_e32 v121, v121
	v_lshl_or_b32 v0, v123, 8, v0
	v_fma_f32 v123, v124, s49, 0.5
	v_fma_f32 v124, v125, s49, 0.5
	v_fma_f32 v118, v118, s49, 0.5
	v_fma_f32 v119, v119, s49, 0.5
	v_max_f32_e32 v123, 1.0, v123
	v_max_f32_e32 v124, 1.0, v124
	v_max_f32_e32 v118, 1.0, v118
	v_max_f32_e32 v119, 1.0, v119
	v_fma_f32 v120, v120, s49, 0.5
	v_fma_f32 v121, v121, s49, 0.5
	v_cvt_u32_f32_sdwa v123, v123 dst_sel:WORD_1 dst_unused:UNUSED_PAD src0_sel:DWORD
	v_cvt_u32_f32_sdwa v124, v124 dst_sel:BYTE_3 dst_unused:UNUSED_PAD src0_sel:DWORD
	v_cvt_u32_f32_e32 v118, v118
	v_cvt_u32_f32_e32 v119, v119
	v_max_f32_e32 v120, 1.0, v120
	v_max_f32_e32 v121, 1.0, v121
	v_mul_f32_e32 v114, 0xba38aa3b, v114
	v_cvt_u32_f32_sdwa v120, v120 dst_sel:WORD_1 dst_unused:UNUSED_PAD src0_sel:DWORD
	v_cvt_u32_f32_sdwa v121, v121 dst_sel:BYTE_3 dst_unused:UNUSED_PAD src0_sel:DWORD
	v_exp_f32_e32 v114, v114
	v_or3_b32 v123, v0, v123, v124
	v_lshl_or_b32 v0, v119, 8, v118
	v_or3_b32 v124, v0, v120, v121
	v_add_f32_e32 v0, 1.0, v114
	v_mul_f32_e32 v114, 0xba38aa3b, v115
	v_exp_f32_e32 v114, v114
	v_mul_f32_e32 v115, 0xba38aa3b, v116
	v_rcp_f32_e32 v0, v0
	v_mul_f32_e32 v116, 0xba38aa3b, v117
	v_add_f32_e32 v114, 1.0, v114
	v_rcp_f32_e32 v114, v114
	v_exp_f32_e32 v115, v115
	v_exp_f32_e32 v116, v116
	v_fma_f32 v0, v0, s49, 0.5
	v_fma_f32 v114, v114, s49, 0.5
	v_add_f32_e32 v115, 1.0, v115
	v_max_f32_e32 v0, 1.0, v0
	v_max_f32_e32 v114, 1.0, v114
	v_add_f32_e32 v116, 1.0, v116
	v_cvt_u32_f32_e32 v0, v0
	v_cvt_u32_f32_e32 v114, v114
	v_rcp_f32_e32 v115, v115
	v_rcp_f32_e32 v116, v116
	v_mul_f32_e32 v110, 0xba38aa3b, v110
	v_lshl_or_b32 v0, v114, 8, v0
	v_fma_f32 v114, v115, s49, 0.5
	v_fma_f32 v115, v116, s49, 0.5
	v_max_f32_e32 v114, 1.0, v114
	v_max_f32_e32 v115, 1.0, v115
	v_mul_f32_e32 v111, 0xba38aa3b, v111
	v_cvt_u32_f32_sdwa v114, v114 dst_sel:WORD_1 dst_unused:UNUSED_PAD src0_sel:DWORD
	v_cvt_u32_f32_sdwa v115, v115 dst_sel:BYTE_3 dst_unused:UNUSED_PAD src0_sel:DWORD
	v_exp_f32_e32 v110, v110
; #define GAS __attribute__((address_space(1)))
; __device__ __forceinline__ unsigned gate_q8(float g) { return (unsigned)fmaxf(g * 255.0f + 0.5f, 1.0f); }
; __device__ __forceinline__ unsigned gate_pk4(const f32x4& g) { return gate_q8(g[0]) | (gate_q8(g[1]) << 8) | (gate_q8(g[2]) << 16) | (gate_q8(g[3]) << 24); }
;     __device__ __forceinline__ void operator()(const f32x4 (&acc)[2][2][4][2], const pg8::GUnit& u, int wr, int wc, int fr, int fq) const {
;     ...
;         for (int ai = 0; ai < 2; ++ai)
; #pragma unroll
;             for (int m = 0; m < 4; ++m) { u32x4 w; unsigned wq[4];
; #pragma unroll
;                 for (int bj = 0; bj < 2; ++bj)
; #pragma unroll
;                     for (int n = 0; n < 2; ++n) { f32x4 v = acc[ai][bj][m][n];
; #pragma unroll
;                         for (int j = 0; j < 4; ++j) v[j] = __builtin_amdgcn_rcpf(1.0f + __builtin_amdgcn_exp2f(v[j] * (-LOG2E * G8_DESCALE)));
;                         wq[bj * 2 + n] = gate_pk4(v); }
;                 w.x = wq[0]; w.y = wq[1]; w.z = wq[2]; w.w = wq[3];
;                 *(GAS u32x4*)(gb + (size_t)((ai * 4 + m) * 4) * (INW * 2)) = w; }
	v_exp_f32_e32 v111, v111
	v_mul_f32_e32 v106, 0xba38aa3b, v106
	v_or3_b32 v125, v0, v114, v115
	v_add_f32_e32 v0, 1.0, v110
	v_add_f32_e32 v110, 1.0, v111
	v_mul_f32_e32 v111, 0xba38aa3b, v112
	v_mul_f32_e32 v112, 0xba38aa3b, v113
	v_exp_f32_e32 v111, v111
	v_exp_f32_e32 v112, v112
	v_rcp_f32_e32 v0, v0
	v_rcp_f32_e32 v110, v110
	v_add_f32_e32 v111, 1.0, v111
	v_add_f32_e32 v112, 1.0, v112
	v_rcp_f32_e32 v111, v111
	v_rcp_f32_e32 v112, v112
	v_fma_f32 v0, v0, s49, 0.5
	v_fma_f32 v110, v110, s49, 0.5
	v_max_f32_e32 v0, 1.0, v0
	v_max_f32_e32 v110, 1.0, v110
	v_fma_f32 v111, v111, s49, 0.5
	v_fma_f32 v112, v112, s49, 0.5
	v_cvt_u32_f32_e32 v0, v0
	v_cvt_u32_f32_e32 v110, v110
	v_max_f32_e32 v111, 1.0, v111
	v_max_f32_e32 v112, 1.0, v112
	v_mul_f32_e32 v107, 0xba38aa3b, v107
	v_cvt_u32_f32_sdwa v111, v111 dst_sel:WORD_1 dst_unused:UNUSED_PAD src0_sel:DWORD
	v_cvt_u32_f32_sdwa v112, v112 dst_sel:BYTE_3 dst_unused:UNUSED_PAD src0_sel:DWORD
	v_exp_f32_e32 v113, v106
	v_exp_f32_e32 v107, v107
	v_lshl_or_b32 v0, v110, 8, v0
	v_or3_b32 v106, v0, v111, v112
	v_add_f32_e32 v0, 1.0, v113
	v_add_f32_e32 v107, 1.0, v107
	v_mul_f32_e32 v108, 0xba38aa3b, v108
	v_rcp_f32_e32 v0, v0
	v_rcp_f32_e32 v107, v107
	v_mul_f32_e32 v109, 0xba38aa3b, v109
	v_exp_f32_e32 v108, v108
	v_exp_f32_e32 v109, v109
	v_fma_f32 v0, v0, s49, 0.5
	v_fma_f32 v107, v107, s49, 0.5
	v_add_f32_e32 v108, 1.0, v108
	v_max_f32_e32 v0, 1.0, v0
	v_max_f32_e32 v107, 1.0, v107
	v_add_f32_e32 v109, 1.0, v109
	v_cvt_u32_f32_e32 v0, v0
	v_cvt_u32_f32_e32 v107, v107
	v_rcp_f32_e32 v108, v108
	v_rcp_f32_e32 v109, v109
	v_mul_f32_e32 v102, 0xba38aa3b, v102
	v_lshl_or_b32 v0, v107, 8, v0
	v_fma_f32 v107, v108, s49, 0.5
	v_fma_f32 v108, v109, s49, 0.5
	v_max_f32_e32 v107, 1.0, v107
	v_max_f32_e32 v108, 1.0, v108
	v_mul_f32_e32 v103, 0xba38aa3b, v103
	v_cvt_u32_f32_sdwa v107, v107 dst_sel:WORD_1 dst_unused:UNUSED_PAD src0_sel:DWORD
	v_cvt_u32_f32_sdwa v108, v108 dst_sel:BYTE_3 dst_unused:UNUSED_PAD src0_sel:DWORD
	v_exp_f32_e32 v102, v102
	v_exp_f32_e32 v103, v103
	v_mul_f32_e32 v98, 0xba38aa3b, v98
	v_or3_b32 v107, v0, v107, v108
	v_add_f32_e32 v0, 1.0, v102
	v_add_f32_e32 v102, 1.0, v103
	v_mul_f32_e32 v103, 0xba38aa3b, v104
	v_mul_f32_e32 v104, 0xba38aa3b, v105
	v_mul_f32_e32 v99, 0xba38aa3b, v99
	v_exp_f32_e32 v103, v103
	v_exp_f32_e32 v104, v104
	v_exp_f32_e32 v98, v98
	v_exp_f32_e32 v99, v99
	v_mul_f32_e32 v100, 0xba38aa3b, v100
	v_mul_f32_e32 v101, 0xba38aa3b, v101
	v_exp_f32_e32 v100, v100
	v_exp_f32_e32 v101, v101
	v_rcp_f32_e32 v0, v0
	v_rcp_f32_e32 v102, v102
	v_add_f32_e32 v103, 1.0, v103
	v_add_f32_e32 v104, 1.0, v104
	v_add_f32_e32 v98, 1.0, v98
	v_add_f32_e32 v99, 1.0, v99
	v_rcp_f32_e32 v103, v103
	v_rcp_f32_e32 v104, v104
	v_rcp_f32_e32 v98, v98
	v_rcp_f32_e32 v99, v99
	v_add_f32_e32 v100, 1.0, v100
	v_add_f32_e32 v101, 1.0, v101
	v_rcp_f32_e32 v100, v100
	v_rcp_f32_e32 v101, v101
	v_fma_f32 v0, v0, s49, 0.5
	v_fma_f32 v102, v102, s49, 0.5
	v_max_f32_e32 v0, 1.0, v0
	v_max_f32_e32 v102, 1.0, v102
	v_fma_f32 v103, v103, s49, 0.5
	v_fma_f32 v104, v104, s49, 0.5
	v_fma_f32 v98, v98, s49, 0.5
	v_fma_f32 v99, v99, s49, 0.5
	v_cvt_u32_f32_e32 v0, v0
	v_cvt_u32_f32_e32 v102, v102
	v_max_f32_e32 v103, 1.0, v103
	v_max_f32_e32 v104, 1.0, v104
	v_max_f32_e32 v98, 1.0, v98
	v_max_f32_e32 v99, 1.0, v99
	v_fma_f32 v100, v100, s49, 0.5
	v_fma_f32 v101, v101, s49, 0.5
	v_cvt_u32_f32_sdwa v103, v103 dst_sel:WORD_1 dst_unused:UNUSED_PAD src0_sel:DWORD
	v_cvt_u32_f32_sdwa v104, v104 dst_sel:BYTE_3 dst_unused:UNUSED_PAD src0_sel:DWORD
	v_cvt_u32_f32_e32 v98, v98
	v_cvt_u32_f32_e32 v99, v99
	v_max_f32_e32 v100, 1.0, v100
	v_max_f32_e32 v101, 1.0, v101
	v_cvt_u32_f32_sdwa v100, v100 dst_sel:WORD_1 dst_unused:UNUSED_PAD src0_sel:DWORD
	v_cvt_u32_f32_sdwa v101, v101 dst_sel:BYTE_3 dst_unused:UNUSED_PAD src0_sel:DWORD
	v_lshl_or_b32 v0, v102, 8, v0
	v_or3_b32 v108, v0, v103, v104
	v_lshl_or_b32 v0, v99, 8, v98
	v_or3_b32 v109, v0, v100, v101
	v_mul_f32_e32 v0, 0xba38aa3b, v94
	v_mul_f32_e32 v94, 0xba38aa3b, v95
	v_exp_f32_e32 v0, v0
	v_exp_f32_e32 v98, v94
	v_mul_f32_e32 v96, 0xba38aa3b, v96
	v_mul_f32_e32 v97, 0xba38aa3b, v97
	v_exp_f32_e32 v96, v96
	v_exp_f32_e32 v97, v97
	v_add_f32_e32 v0, 1.0, v0
	v_add_f32_e32 v98, 1.0, v98
	v_rcp_f32_e32 v0, v0
	v_rcp_f32_e32 v98, v98
	v_add_f32_e32 v96, 1.0, v96
	v_add_f32_e32 v97, 1.0, v97
	v_rcp_f32_e32 v96, v96
	v_rcp_f32_e32 v97, v97
	v_fma_f32 v0, v0, s49, 0.5
	v_fma_f32 v98, v98, s49, 0.5
	v_max_f32_e32 v0, 1.0, v0
	v_max_f32_e32 v98, 1.0, v98
	v_fma_f32 v96, v96, s49, 0.5
	v_fma_f32 v97, v97, s49, 0.5
	v_cvt_u32_f32_e32 v0, v0
	v_cvt_u32_f32_e32 v98, v98
	v_max_f32_e32 v96, 1.0, v96
	v_max_f32_e32 v97, 1.0, v97
	v_mul_f32_e32 v90, 0xba38aa3b, v90
	v_mul_f32_e32 v91, 0xba38aa3b, v91
	v_cvt_u32_f32_sdwa v96, v96 dst_sel:WORD_1 dst_unused:UNUSED_PAD src0_sel:DWORD
	v_cvt_u32_f32_sdwa v97, v97 dst_sel:BYTE_3 dst_unused:UNUSED_PAD src0_sel:DWORD
	v_exp_f32_e32 v99, v90
	v_exp_f32_e32 v91, v91
	v_lshl_or_b32 v0, v98, 8, v0
	v_or3_b32 v90, v0, v96, v97
	v_add_f32_e32 v0, 1.0, v99
	v_add_f32_e32 v91, 1.0, v91
	v_mul_f32_e32 v92, 0xba38aa3b, v92
	v_rcp_f32_e32 v0, v0
	v_rcp_f32_e32 v91, v91
	v_mul_f32_e32 v93, 0xba38aa3b, v93
	v_exp_f32_e32 v92, v92
	v_exp_f32_e32 v93, v93
	v_fma_f32 v0, v0, s49, 0.5
	v_fma_f32 v91, v91, s49, 0.5
	v_add_f32_e32 v92, 1.0, v92
	v_max_f32_e32 v0, 1.0, v0
	v_max_f32_e32 v91, 1.0, v91
	v_add_f32_e32 v93, 1.0, v93
	v_cvt_u32_f32_e32 v0, v0
	v_cvt_u32_f32_e32 v91, v91
	v_rcp_f32_e32 v92, v92
	v_rcp_f32_e32 v93, v93
	v_mul_f32_e32 v86, 0xba38aa3b, v86
	v_lshl_or_b32 v0, v91, 8, v0
	v_fma_f32 v91, v92, s49, 0.5
	v_fma_f32 v92, v93, s49, 0.5
; #define GAS __attribute__((address_space(1)))
; __device__ __forceinline__ unsigned gate_q8(float g) { return (unsigned)fmaxf(g * 255.0f + 0.5f, 1.0f); }
; __device__ __forceinline__ unsigned gate_pk4(const f32x4& g) { return gate_q8(g[0]) | (gate_q8(g[1]) << 8) | (gate_q8(g[2]) << 16) | (gate_q8(g[3]) << 24); }
;     __device__ __forceinline__ void operator()(const f32x4 (&acc)[2][2][4][2], const pg8::GUnit& u, int wr, int wc, int fr, int fq) const {
;     ...
;         for (int ai = 0; ai < 2; ++ai)
; #pragma unroll
;             for (int m = 0; m < 4; ++m) { u32x4 w; unsigned wq[4];
; #pragma unroll
;                 for (int bj = 0; bj < 2; ++bj)
; #pragma unroll
;                     for (int n = 0; n < 2; ++n) { f32x4 v = acc[ai][bj][m][n];
; #pragma unroll
;                         for (int j = 0; j < 4; ++j) v[j] = __builtin_amdgcn_rcpf(1.0f + __builtin_amdgcn_exp2f(v[j] * (-LOG2E * G8_DESCALE)));
;                         wq[bj * 2 + n] = gate_pk4(v); }
;                 w.x = wq[0]; w.y = wq[1]; w.z = wq[2]; w.w = wq[3];
;                 *(GAS u32x4*)(gb + (size_t)((ai * 4 + m) * 4) * (INW * 2)) = w; }
	v_max_f32_e32 v91, 1.0, v91
	v_max_f32_e32 v92, 1.0, v92
	v_mul_f32_e32 v87, 0xba38aa3b, v87
	v_cvt_u32_f32_sdwa v91, v91 dst_sel:WORD_1 dst_unused:UNUSED_PAD src0_sel:DWORD
	v_cvt_u32_f32_sdwa v92, v92 dst_sel:BYTE_3 dst_unused:UNUSED_PAD src0_sel:DWORD
	v_exp_f32_e32 v86, v86
	v_exp_f32_e32 v87, v87
	v_mul_f32_e32 v82, 0xba38aa3b, v82
	v_or3_b32 v91, v0, v91, v92
	v_add_f32_e32 v0, 1.0, v86
	v_add_f32_e32 v86, 1.0, v87
	v_mul_f32_e32 v87, 0xba38aa3b, v88
	v_mul_f32_e32 v88, 0xba38aa3b, v89
	v_mul_f32_e32 v83, 0xba38aa3b, v83
	v_exp_f32_e32 v87, v87
	v_exp_f32_e32 v88, v88
	v_exp_f32_e32 v82, v82
	v_exp_f32_e32 v83, v83
	v_mul_f32_e32 v84, 0xba38aa3b, v84
	v_mul_f32_e32 v85, 0xba38aa3b, v85
	v_exp_f32_e32 v84, v84
	v_exp_f32_e32 v85, v85
	v_rcp_f32_e32 v0, v0
	v_rcp_f32_e32 v86, v86
	v_add_f32_e32 v87, 1.0, v87
	v_add_f32_e32 v88, 1.0, v88
	v_add_f32_e32 v82, 1.0, v82
	v_add_f32_e32 v83, 1.0, v83
	v_rcp_f32_e32 v87, v87
	v_rcp_f32_e32 v88, v88
	v_rcp_f32_e32 v82, v82
	v_rcp_f32_e32 v83, v83
	v_add_f32_e32 v84, 1.0, v84
	v_add_f32_e32 v85, 1.0, v85
	v_rcp_f32_e32 v84, v84
	v_rcp_f32_e32 v85, v85
	v_fma_f32 v0, v0, s49, 0.5
	v_fma_f32 v86, v86, s49, 0.5
	v_max_f32_e32 v0, 1.0, v0
	v_max_f32_e32 v86, 1.0, v86
	v_fma_f32 v87, v87, s49, 0.5
	v_fma_f32 v88, v88, s49, 0.5
	v_fma_f32 v82, v82, s49, 0.5
	v_fma_f32 v83, v83, s49, 0.5
	v_cvt_u32_f32_e32 v0, v0
	v_cvt_u32_f32_e32 v86, v86
	v_max_f32_e32 v87, 1.0, v87
	v_max_f32_e32 v88, 1.0, v88
	v_max_f32_e32 v82, 1.0, v82
	v_max_f32_e32 v83, 1.0, v83
	v_fma_f32 v84, v84, s49, 0.5
	v_fma_f32 v85, v85, s49, 0.5
	v_cvt_u32_f32_sdwa v87, v87 dst_sel:WORD_1 dst_unused:UNUSED_PAD src0_sel:DWORD
	v_cvt_u32_f32_sdwa v88, v88 dst_sel:BYTE_3 dst_unused:UNUSED_PAD src0_sel:DWORD
	v_cvt_u32_f32_e32 v82, v82
	v_cvt_u32_f32_e32 v83, v83
	v_max_f32_e32 v84, 1.0, v84
	v_max_f32_e32 v85, 1.0, v85
	v_cvt_u32_f32_sdwa v84, v84 dst_sel:WORD_1 dst_unused:UNUSED_PAD src0_sel:DWORD
	v_cvt_u32_f32_sdwa v85, v85 dst_sel:BYTE_3 dst_unused:UNUSED_PAD src0_sel:DWORD
	v_lshl_or_b32 v0, v86, 8, v0
	v_or3_b32 v92, v0, v87, v88
	v_lshl_or_b32 v0, v83, 8, v82
	v_or3_b32 v93, v0, v84, v85
	v_mul_f32_e32 v0, 0xba38aa3b, v78
	v_mul_f32_e32 v78, 0xba38aa3b, v79
	v_exp_f32_e32 v0, v0
	v_exp_f32_e32 v82, v78
	v_mul_f32_e32 v80, 0xba38aa3b, v80
	v_mul_f32_e32 v81, 0xba38aa3b, v81
	v_exp_f32_e32 v80, v80
	v_exp_f32_e32 v81, v81
	v_add_f32_e32 v0, 1.0, v0
	v_add_f32_e32 v82, 1.0, v82
	v_rcp_f32_e32 v0, v0
	v_rcp_f32_e32 v82, v82
	v_add_f32_e32 v80, 1.0, v80
	v_add_f32_e32 v81, 1.0, v81
	v_rcp_f32_e32 v80, v80
	v_rcp_f32_e32 v81, v81
	v_fma_f32 v0, v0, s49, 0.5
	v_fma_f32 v82, v82, s49, 0.5
	v_max_f32_e32 v0, 1.0, v0
	v_max_f32_e32 v82, 1.0, v82
	v_fma_f32 v80, v80, s49, 0.5
	v_fma_f32 v81, v81, s49, 0.5
	v_cvt_u32_f32_e32 v0, v0
	v_cvt_u32_f32_e32 v82, v82
	v_max_f32_e32 v80, 1.0, v80
	v_max_f32_e32 v81, 1.0, v81
	v_mul_f32_e32 v74, 0xba38aa3b, v74
	v_mul_f32_e32 v75, 0xba38aa3b, v75
	v_cvt_u32_f32_sdwa v80, v80 dst_sel:WORD_1 dst_unused:UNUSED_PAD src0_sel:DWORD
	v_cvt_u32_f32_sdwa v81, v81 dst_sel:BYTE_3 dst_unused:UNUSED_PAD src0_sel:DWORD
	v_exp_f32_e32 v83, v74
	v_exp_f32_e32 v75, v75
	v_lshl_or_b32 v0, v82, 8, v0
	v_or3_b32 v74, v0, v80, v81
	v_add_f32_e32 v0, 1.0, v83
	v_add_f32_e32 v75, 1.0, v75
	v_mul_f32_e32 v76, 0xba38aa3b, v76
	v_rcp_f32_e32 v0, v0
	v_rcp_f32_e32 v75, v75
	v_mul_f32_e32 v77, 0xba38aa3b, v77
	v_exp_f32_e32 v76, v76
	v_exp_f32_e32 v77, v77
	v_fma_f32 v0, v0, s49, 0.5
	v_fma_f32 v75, v75, s49, 0.5
	v_add_f32_e32 v76, 1.0, v76
	v_max_f32_e32 v0, 1.0, v0
	v_max_f32_e32 v75, 1.0, v75
	v_add_f32_e32 v77, 1.0, v77
	v_cvt_u32_f32_e32 v0, v0
	v_cvt_u32_f32_e32 v75, v75
	v_rcp_f32_e32 v76, v76
	v_rcp_f32_e32 v77, v77
	v_mul_f32_e32 v70, 0xba38aa3b, v70
	v_lshl_or_b32 v0, v75, 8, v0
	v_fma_f32 v75, v76, s49, 0.5
	v_fma_f32 v76, v77, s49, 0.5
	v_max_f32_e32 v75, 1.0, v75
	v_max_f32_e32 v76, 1.0, v76
	v_mul_f32_e32 v71, 0xba38aa3b, v71
	v_cvt_u32_f32_sdwa v75, v75 dst_sel:WORD_1 dst_unused:UNUSED_PAD src0_sel:DWORD
	v_cvt_u32_f32_sdwa v76, v76 dst_sel:BYTE_3 dst_unused:UNUSED_PAD src0_sel:DWORD
	v_exp_f32_e32 v70, v70
	v_exp_f32_e32 v71, v71
	v_mul_f32_e32 v66, 0xba38aa3b, v66
	v_or3_b32 v75, v0, v75, v76
	v_add_f32_e32 v0, 1.0, v70
	v_add_f32_e32 v70, 1.0, v71
	v_mul_f32_e32 v71, 0xba38aa3b, v72
	v_mul_f32_e32 v72, 0xba38aa3b, v73
	v_mul_f32_e32 v67, 0xba38aa3b, v67
	v_exp_f32_e32 v71, v71
	v_exp_f32_e32 v72, v72
	v_exp_f32_e32 v66, v66
	v_exp_f32_e32 v67, v67
	v_mul_f32_e32 v68, 0xba38aa3b, v68
	v_mul_f32_e32 v69, 0xba38aa3b, v69
	v_exp_f32_e32 v68, v68
	v_exp_f32_e32 v69, v69
	v_rcp_f32_e32 v0, v0
	v_rcp_f32_e32 v70, v70
	v_add_f32_e32 v71, 1.0, v71
	v_add_f32_e32 v72, 1.0, v72
	v_add_f32_e32 v66, 1.0, v66
	v_add_f32_e32 v67, 1.0, v67
	v_rcp_f32_e32 v71, v71
	v_rcp_f32_e32 v72, v72
	v_rcp_f32_e32 v66, v66
	v_rcp_f32_e32 v67, v67
	v_add_f32_e32 v68, 1.0, v68
	v_add_f32_e32 v69, 1.0, v69
	v_rcp_f32_e32 v68, v68
	v_rcp_f32_e32 v69, v69
	v_fma_f32 v0, v0, s49, 0.5
	v_fma_f32 v70, v70, s49, 0.5
	v_max_f32_e32 v0, 1.0, v0
	v_max_f32_e32 v70, 1.0, v70
	v_fma_f32 v71, v71, s49, 0.5
	v_fma_f32 v72, v72, s49, 0.5
	v_fma_f32 v66, v66, s49, 0.5
	v_fma_f32 v67, v67, s49, 0.5
	v_cvt_u32_f32_e32 v0, v0
	v_cvt_u32_f32_e32 v70, v70
	v_max_f32_e32 v71, 1.0, v71
	v_max_f32_e32 v72, 1.0, v72
	v_max_f32_e32 v66, 1.0, v66
	v_max_f32_e32 v67, 1.0, v67
	v_fma_f32 v68, v68, s49, 0.5
	v_fma_f32 v69, v69, s49, 0.5
	v_cvt_u32_f32_sdwa v71, v71 dst_sel:WORD_1 dst_unused:UNUSED_PAD src0_sel:DWORD
	v_cvt_u32_f32_sdwa v72, v72 dst_sel:BYTE_3 dst_unused:UNUSED_PAD src0_sel:DWORD
	v_cvt_u32_f32_e32 v66, v66
	v_cvt_u32_f32_e32 v67, v67
; #define GAS __attribute__((address_space(1)))
; __device__ __forceinline__ unsigned gate_q8(float g) { return (unsigned)fmaxf(g * 255.0f + 0.5f, 1.0f); }
; __device__ __forceinline__ unsigned gate_pk4(const f32x4& g) { return gate_q8(g[0]) | (gate_q8(g[1]) << 8) | (gate_q8(g[2]) << 16) | (gate_q8(g[3]) << 24); }
;     __device__ __forceinline__ void operator()(const f32x4 (&acc)[2][2][4][2], const pg8::GUnit& u, int wr, int wc, int fr, int fq) const {
;     ...
;         for (int ai = 0; ai < 2; ++ai)
; #pragma unroll
;             for (int m = 0; m < 4; ++m) { u32x4 w; unsigned wq[4];
; #pragma unroll
;                 for (int bj = 0; bj < 2; ++bj)
; #pragma unroll
;                     for (int n = 0; n < 2; ++n) { f32x4 v = acc[ai][bj][m][n];
; #pragma unroll
;                         for (int j = 0; j < 4; ++j) v[j] = __builtin_amdgcn_rcpf(1.0f + __builtin_amdgcn_exp2f(v[j] * (-LOG2E * G8_DESCALE)));
;                         wq[bj * 2 + n] = gate_pk4(v); }
;                 w.x = wq[0]; w.y = wq[1]; w.z = wq[2]; w.w = wq[3];
;                 *(GAS u32x4*)(gb + (size_t)((ai * 4 + m) * 4) * (INW * 2)) = w; }
	v_max_f32_e32 v68, 1.0, v68
	v_max_f32_e32 v69, 1.0, v69
	v_cvt_u32_f32_sdwa v68, v68 dst_sel:WORD_1 dst_unused:UNUSED_PAD src0_sel:DWORD
	v_cvt_u32_f32_sdwa v69, v69 dst_sel:BYTE_3 dst_unused:UNUSED_PAD src0_sel:DWORD
	v_lshl_or_b32 v0, v70, 8, v0
	v_or3_b32 v76, v0, v71, v72
	v_lshl_or_b32 v0, v67, 8, v66
	v_or3_b32 v77, v0, v68, v69
	v_mul_f32_e32 v0, 0xba38aa3b, v62
	v_mul_f32_e32 v62, 0xba38aa3b, v63
	v_exp_f32_e32 v0, v0
	v_exp_f32_e32 v66, v62
	v_mul_f32_e32 v64, 0xba38aa3b, v64
	v_mul_f32_e32 v65, 0xba38aa3b, v65
	v_exp_f32_e32 v64, v64
	v_exp_f32_e32 v65, v65
	v_add_f32_e32 v0, 1.0, v0
	v_add_f32_e32 v66, 1.0, v66
	v_rcp_f32_e32 v0, v0
	v_rcp_f32_e32 v66, v66
	v_add_f32_e32 v64, 1.0, v64
	v_add_f32_e32 v65, 1.0, v65
	v_rcp_f32_e32 v64, v64
	v_rcp_f32_e32 v65, v65
	v_fma_f32 v0, v0, s49, 0.5
	v_fma_f32 v66, v66, s49, 0.5
	v_max_f32_e32 v0, 1.0, v0
	v_max_f32_e32 v66, 1.0, v66
	v_fma_f32 v64, v64, s49, 0.5
	v_fma_f32 v65, v65, s49, 0.5
	v_cvt_u32_f32_e32 v0, v0
	v_cvt_u32_f32_e32 v66, v66
	v_max_f32_e32 v64, 1.0, v64
	v_max_f32_e32 v65, 1.0, v65
	v_mul_f32_e32 v58, 0xba38aa3b, v58
	v_mul_f32_e32 v59, 0xba38aa3b, v59
	v_cvt_u32_f32_sdwa v64, v64 dst_sel:WORD_1 dst_unused:UNUSED_PAD src0_sel:DWORD
	v_cvt_u32_f32_sdwa v65, v65 dst_sel:BYTE_3 dst_unused:UNUSED_PAD src0_sel:DWORD
	v_exp_f32_e32 v67, v58
	v_exp_f32_e32 v59, v59
	v_lshl_or_b32 v0, v66, 8, v0
	v_or3_b32 v58, v0, v64, v65
	v_add_f32_e32 v0, 1.0, v67
	v_add_f32_e32 v59, 1.0, v59
	v_mul_f32_e32 v60, 0xba38aa3b, v60
	v_rcp_f32_e32 v0, v0
	v_rcp_f32_e32 v59, v59
	v_mul_f32_e32 v61, 0xba38aa3b, v61
	v_exp_f32_e32 v60, v60
	v_exp_f32_e32 v61, v61
	v_fma_f32 v0, v0, s49, 0.5
	v_fma_f32 v59, v59, s49, 0.5
	v_add_f32_e32 v60, 1.0, v60
	v_max_f32_e32 v0, 1.0, v0
	v_max_f32_e32 v59, 1.0, v59
	v_add_f32_e32 v61, 1.0, v61
	v_cvt_u32_f32_e32 v0, v0
	v_cvt_u32_f32_e32 v59, v59
	v_rcp_f32_e32 v60, v60
	v_rcp_f32_e32 v61, v61
	v_mul_f32_e32 v54, 0xba38aa3b, v54
	v_lshl_or_b32 v0, v59, 8, v0
	v_fma_f32 v59, v60, s49, 0.5
	v_fma_f32 v60, v61, s49, 0.5
	v_max_f32_e32 v59, 1.0, v59
	v_max_f32_e32 v60, 1.0, v60
	v_mul_f32_e32 v55, 0xba38aa3b, v55
	v_cvt_u32_f32_sdwa v59, v59 dst_sel:WORD_1 dst_unused:UNUSED_PAD src0_sel:DWORD
	v_cvt_u32_f32_sdwa v60, v60 dst_sel:BYTE_3 dst_unused:UNUSED_PAD src0_sel:DWORD
	v_exp_f32_e32 v54, v54
	v_exp_f32_e32 v55, v55
	v_mul_f32_e32 v50, 0xba38aa3b, v50
	v_or3_b32 v59, v0, v59, v60
	v_add_f32_e32 v0, 1.0, v54
	v_add_f32_e32 v54, 1.0, v55
	v_mul_f32_e32 v55, 0xba38aa3b, v56
	v_mul_f32_e32 v56, 0xba38aa3b, v57
	v_mul_f32_e32 v51, 0xba38aa3b, v51
	v_exp_f32_e32 v55, v55
	v_exp_f32_e32 v56, v56
	v_exp_f32_e32 v50, v50
	v_exp_f32_e32 v51, v51
	v_mul_f32_e32 v52, 0xba38aa3b, v52
	v_mul_f32_e32 v53, 0xba38aa3b, v53
	v_exp_f32_e32 v52, v52
	v_exp_f32_e32 v53, v53
	v_rcp_f32_e32 v0, v0
	v_rcp_f32_e32 v54, v54
	v_add_f32_e32 v55, 1.0, v55
	v_add_f32_e32 v56, 1.0, v56
	v_add_f32_e32 v50, 1.0, v50
	v_add_f32_e32 v51, 1.0, v51
	v_rcp_f32_e32 v55, v55
	v_rcp_f32_e32 v56, v56
	v_rcp_f32_e32 v50, v50
	v_rcp_f32_e32 v51, v51
	v_add_f32_e32 v52, 1.0, v52
	v_add_f32_e32 v53, 1.0, v53
	v_rcp_f32_e32 v52, v52
	v_rcp_f32_e32 v53, v53
	v_fma_f32 v0, v0, s49, 0.5
	v_fma_f32 v54, v54, s49, 0.5
	v_max_f32_e32 v0, 1.0, v0
	v_max_f32_e32 v54, 1.0, v54
	v_fma_f32 v55, v55, s49, 0.5
	v_fma_f32 v56, v56, s49, 0.5
	v_fma_f32 v50, v50, s49, 0.5
	v_fma_f32 v51, v51, s49, 0.5
	v_cvt_u32_f32_e32 v0, v0
	v_cvt_u32_f32_e32 v54, v54
	v_max_f32_e32 v55, 1.0, v55
	v_max_f32_e32 v56, 1.0, v56
	v_max_f32_e32 v50, 1.0, v50
	v_max_f32_e32 v51, 1.0, v51
	v_fma_f32 v52, v52, s49, 0.5
	v_fma_f32 v53, v53, s49, 0.5
	v_cvt_u32_f32_sdwa v55, v55 dst_sel:WORD_1 dst_unused:UNUSED_PAD src0_sel:DWORD
	v_cvt_u32_f32_sdwa v56, v56 dst_sel:BYTE_3 dst_unused:UNUSED_PAD src0_sel:DWORD
	v_cvt_u32_f32_e32 v50, v50
	v_cvt_u32_f32_e32 v51, v51
	v_max_f32_e32 v52, 1.0, v52
	v_max_f32_e32 v53, 1.0, v53
	v_cvt_u32_f32_sdwa v52, v52 dst_sel:WORD_1 dst_unused:UNUSED_PAD src0_sel:DWORD
	v_cvt_u32_f32_sdwa v53, v53 dst_sel:BYTE_3 dst_unused:UNUSED_PAD src0_sel:DWORD
	v_lshl_or_b32 v0, v54, 8, v0
	v_or3_b32 v60, v0, v55, v56
	v_lshl_or_b32 v0, v51, 8, v50
	v_or3_b32 v61, v0, v52, v53
	v_mul_f32_e32 v0, 0xba38aa3b, v46
	v_mul_f32_e32 v46, 0xba38aa3b, v47
	v_exp_f32_e32 v0, v0
	v_exp_f32_e32 v50, v46
	v_mul_f32_e32 v48, 0xba38aa3b, v48
	v_mul_f32_e32 v49, 0xba38aa3b, v49
	v_exp_f32_e32 v48, v48
	v_exp_f32_e32 v49, v49
	v_add_f32_e32 v0, 1.0, v0
	v_add_f32_e32 v50, 1.0, v50
	v_rcp_f32_e32 v0, v0
	v_rcp_f32_e32 v50, v50
	v_add_f32_e32 v48, 1.0, v48
	v_add_f32_e32 v49, 1.0, v49
	v_rcp_f32_e32 v48, v48
	v_rcp_f32_e32 v49, v49
	v_fma_f32 v0, v0, s49, 0.5
	v_fma_f32 v50, v50, s49, 0.5
	v_max_f32_e32 v0, 1.0, v0
	v_max_f32_e32 v50, 1.0, v50
	v_fma_f32 v48, v48, s49, 0.5
	v_fma_f32 v49, v49, s49, 0.5
	v_cvt_u32_f32_e32 v0, v0
	v_cvt_u32_f32_e32 v50, v50
	v_max_f32_e32 v48, 1.0, v48
	v_max_f32_e32 v49, 1.0, v49
	v_mul_f32_e32 v42, 0xba38aa3b, v42
	v_mul_f32_e32 v43, 0xba38aa3b, v43
	v_cvt_u32_f32_sdwa v48, v48 dst_sel:WORD_1 dst_unused:UNUSED_PAD src0_sel:DWORD
	v_cvt_u32_f32_sdwa v49, v49 dst_sel:BYTE_3 dst_unused:UNUSED_PAD src0_sel:DWORD
	v_exp_f32_e32 v51, v42
	v_exp_f32_e32 v43, v43
	v_lshl_or_b32 v0, v50, 8, v0
	v_or3_b32 v42, v0, v48, v49
	v_add_f32_e32 v0, 1.0, v51
	v_add_f32_e32 v43, 1.0, v43
	v_mul_f32_e32 v44, 0xba38aa3b, v44
	v_rcp_f32_e32 v0, v0
	v_rcp_f32_e32 v43, v43
	v_mul_f32_e32 v45, 0xba38aa3b, v45
	v_exp_f32_e32 v44, v44
	v_exp_f32_e32 v45, v45
	v_fma_f32 v0, v0, s49, 0.5
	v_fma_f32 v43, v43, s49, 0.5
	v_add_f32_e32 v44, 1.0, v44
	v_max_f32_e32 v0, 1.0, v0
	v_max_f32_e32 v43, 1.0, v43
	v_add_f32_e32 v45, 1.0, v45
; #define GAS __attribute__((address_space(1)))
; __device__ __forceinline__ unsigned gate_q8(float g) { return (unsigned)fmaxf(g * 255.0f + 0.5f, 1.0f); }
; __device__ __forceinline__ unsigned gate_pk4(const f32x4& g) { return gate_q8(g[0]) | (gate_q8(g[1]) << 8) | (gate_q8(g[2]) << 16) | (gate_q8(g[3]) << 24); }
;     __device__ __forceinline__ void operator()(const f32x4 (&acc)[2][2][4][2], const pg8::GUnit& u, int wr, int wc, int fr, int fq) const {
;     ...
;         for (int ai = 0; ai < 2; ++ai)
; #pragma unroll
;             for (int m = 0; m < 4; ++m) { u32x4 w; unsigned wq[4];
; #pragma unroll
;                 for (int bj = 0; bj < 2; ++bj)
; #pragma unroll
;                     for (int n = 0; n < 2; ++n) { f32x4 v = acc[ai][bj][m][n];
; #pragma unroll
;                         for (int j = 0; j < 4; ++j) v[j] = __builtin_amdgcn_rcpf(1.0f + __builtin_amdgcn_exp2f(v[j] * (-LOG2E * G8_DESCALE)));
;                         wq[bj * 2 + n] = gate_pk4(v); }
;                 w.x = wq[0]; w.y = wq[1]; w.z = wq[2]; w.w = wq[3];
;                 *(GAS u32x4*)(gb + (size_t)((ai * 4 + m) * 4) * (INW * 2)) = w; }
	v_cvt_u32_f32_e32 v0, v0
	v_cvt_u32_f32_e32 v43, v43
	v_rcp_f32_e32 v44, v44
	v_rcp_f32_e32 v45, v45
	v_mul_f32_e32 v38, 0xba38aa3b, v38
	v_lshl_or_b32 v0, v43, 8, v0
	v_fma_f32 v43, v44, s49, 0.5
	v_fma_f32 v44, v45, s49, 0.5
	v_max_f32_e32 v43, 1.0, v43
	v_max_f32_e32 v44, 1.0, v44
	v_mul_f32_e32 v39, 0xba38aa3b, v39
	v_cvt_u32_f32_sdwa v43, v43 dst_sel:WORD_1 dst_unused:UNUSED_PAD src0_sel:DWORD
	v_cvt_u32_f32_sdwa v44, v44 dst_sel:BYTE_3 dst_unused:UNUSED_PAD src0_sel:DWORD
	v_exp_f32_e32 v38, v38
	v_exp_f32_e32 v39, v39
	v_mul_f32_e32 v34, 0xba38aa3b, v34
	v_or3_b32 v43, v0, v43, v44
	v_add_f32_e32 v0, 1.0, v38
	v_add_f32_e32 v38, 1.0, v39
	v_mul_f32_e32 v39, 0xba38aa3b, v40
	v_mul_f32_e32 v40, 0xba38aa3b, v41
	v_mul_f32_e32 v35, 0xba38aa3b, v35
	v_exp_f32_e32 v39, v39
	v_exp_f32_e32 v40, v40
	v_exp_f32_e32 v34, v34
	v_exp_f32_e32 v35, v35
	v_mul_f32_e32 v36, 0xba38aa3b, v36
	v_mul_f32_e32 v37, 0xba38aa3b, v37
	v_exp_f32_e32 v36, v36
	v_exp_f32_e32 v37, v37
	v_rcp_f32_e32 v0, v0
	v_rcp_f32_e32 v38, v38
	v_add_f32_e32 v39, 1.0, v39
	v_add_f32_e32 v40, 1.0, v40
	v_add_f32_e32 v34, 1.0, v34
	v_add_f32_e32 v35, 1.0, v35
	v_rcp_f32_e32 v39, v39
	v_rcp_f32_e32 v40, v40
	v_rcp_f32_e32 v34, v34
	v_rcp_f32_e32 v35, v35
	v_add_f32_e32 v36, 1.0, v36
	v_add_f32_e32 v37, 1.0, v37
	v_rcp_f32_e32 v36, v36
	v_rcp_f32_e32 v37, v37
	v_fma_f32 v0, v0, s49, 0.5
	v_fma_f32 v38, v38, s49, 0.5
	v_max_f32_e32 v0, 1.0, v0
	v_max_f32_e32 v38, 1.0, v38
	v_fma_f32 v39, v39, s49, 0.5
	v_fma_f32 v40, v40, s49, 0.5
	v_fma_f32 v34, v34, s49, 0.5
	v_fma_f32 v35, v35, s49, 0.5
	v_cvt_u32_f32_e32 v0, v0
	v_cvt_u32_f32_e32 v38, v38
	v_max_f32_e32 v39, 1.0, v39
	v_max_f32_e32 v40, 1.0, v40
	v_max_f32_e32 v34, 1.0, v34
	v_max_f32_e32 v35, 1.0, v35
	v_fma_f32 v36, v36, s49, 0.5
	v_fma_f32 v37, v37, s49, 0.5
	v_cvt_u32_f32_sdwa v39, v39 dst_sel:WORD_1 dst_unused:UNUSED_PAD src0_sel:DWORD
	v_cvt_u32_f32_sdwa v40, v40 dst_sel:BYTE_3 dst_unused:UNUSED_PAD src0_sel:DWORD
	v_cvt_u32_f32_e32 v34, v34
	v_cvt_u32_f32_e32 v35, v35
	v_max_f32_e32 v36, 1.0, v36
	v_max_f32_e32 v37, 1.0, v37
	v_cvt_u32_f32_sdwa v36, v36 dst_sel:WORD_1 dst_unused:UNUSED_PAD src0_sel:DWORD
	v_cvt_u32_f32_sdwa v37, v37 dst_sel:BYTE_3 dst_unused:UNUSED_PAD src0_sel:DWORD
	v_lshl_or_b32 v0, v38, 8, v0
	v_or3_b32 v44, v0, v39, v40
	v_lshl_or_b32 v0, v35, 8, v34
	v_or3_b32 v45, v0, v36, v37
	v_mul_f32_e32 v0, 0xba38aa3b, v30
	v_mul_f32_e32 v30, 0xba38aa3b, v31
	v_exp_f32_e32 v0, v0
	v_exp_f32_e32 v34, v30
	v_mul_f32_e32 v32, 0xba38aa3b, v32
	v_mul_f32_e32 v33, 0xba38aa3b, v33
	v_exp_f32_e32 v32, v32
	v_exp_f32_e32 v33, v33
	v_add_f32_e32 v0, 1.0, v0
	v_add_f32_e32 v34, 1.0, v34
	v_rcp_f32_e32 v0, v0
	v_rcp_f32_e32 v34, v34
	v_add_f32_e32 v32, 1.0, v32
	v_add_f32_e32 v33, 1.0, v33
	v_rcp_f32_e32 v32, v32
	v_rcp_f32_e32 v33, v33
	v_fma_f32 v0, v0, s49, 0.5
	v_fma_f32 v34, v34, s49, 0.5
	v_max_f32_e32 v0, 1.0, v0
	v_max_f32_e32 v34, 1.0, v34
	v_fma_f32 v32, v32, s49, 0.5
	v_fma_f32 v33, v33, s49, 0.5
	v_cvt_u32_f32_e32 v0, v0
	v_cvt_u32_f32_e32 v34, v34
	v_max_f32_e32 v32, 1.0, v32
	v_max_f32_e32 v33, 1.0, v33
	v_mul_f32_e32 v26, 0xba38aa3b, v26
	v_mul_f32_e32 v27, 0xba38aa3b, v27
	v_cvt_u32_f32_sdwa v32, v32 dst_sel:WORD_1 dst_unused:UNUSED_PAD src0_sel:DWORD
	v_cvt_u32_f32_sdwa v33, v33 dst_sel:BYTE_3 dst_unused:UNUSED_PAD src0_sel:DWORD
	v_exp_f32_e32 v35, v26
	v_exp_f32_e32 v27, v27
	v_lshl_or_b32 v0, v34, 8, v0
	v_or3_b32 v26, v0, v32, v33
	v_add_f32_e32 v0, 1.0, v35
	v_add_f32_e32 v27, 1.0, v27
	v_mul_f32_e32 v28, 0xba38aa3b, v28
	v_rcp_f32_e32 v0, v0
	v_rcp_f32_e32 v27, v27
	v_mul_f32_e32 v29, 0xba38aa3b, v29
	v_exp_f32_e32 v28, v28
	v_exp_f32_e32 v29, v29
	v_fma_f32 v0, v0, s49, 0.5
	v_fma_f32 v27, v27, s49, 0.5
	v_add_f32_e32 v28, 1.0, v28
	v_max_f32_e32 v0, 1.0, v0
	v_max_f32_e32 v27, 1.0, v27
	v_add_f32_e32 v29, 1.0, v29
	v_cvt_u32_f32_e32 v0, v0
	v_cvt_u32_f32_e32 v27, v27
	v_rcp_f32_e32 v28, v28
	v_rcp_f32_e32 v29, v29
	v_mul_f32_e32 v22, 0xba38aa3b, v22
	v_lshl_or_b32 v0, v27, 8, v0
	v_fma_f32 v27, v28, s49, 0.5
	v_fma_f32 v28, v29, s49, 0.5
	v_max_f32_e32 v27, 1.0, v27
	v_max_f32_e32 v28, 1.0, v28
	v_mul_f32_e32 v23, 0xba38aa3b, v23
	v_cvt_u32_f32_sdwa v27, v27 dst_sel:WORD_1 dst_unused:UNUSED_PAD src0_sel:DWORD
	v_cvt_u32_f32_sdwa v28, v28 dst_sel:BYTE_3 dst_unused:UNUSED_PAD src0_sel:DWORD
	v_exp_f32_e32 v22, v22
	v_exp_f32_e32 v23, v23
	v_mul_f32_e32 v18, 0xba38aa3b, v18
	v_or3_b32 v27, v0, v27, v28
	v_add_f32_e32 v0, 1.0, v22
	v_add_f32_e32 v22, 1.0, v23
	v_mul_f32_e32 v23, 0xba38aa3b, v24
	v_mul_f32_e32 v24, 0xba38aa3b, v25
	v_mul_f32_e32 v19, 0xba38aa3b, v19
	v_exp_f32_e32 v23, v23
	v_exp_f32_e32 v24, v24
	v_exp_f32_e32 v18, v18
	v_exp_f32_e32 v19, v19
	v_mul_f32_e32 v20, 0xba38aa3b, v20
	v_mul_f32_e32 v21, 0xba38aa3b, v21
	v_exp_f32_e32 v20, v20
	v_exp_f32_e32 v21, v21
	v_rcp_f32_e32 v0, v0
	v_rcp_f32_e32 v22, v22
	v_add_f32_e32 v23, 1.0, v23
	v_add_f32_e32 v24, 1.0, v24
	v_add_f32_e32 v18, 1.0, v18
	v_add_f32_e32 v19, 1.0, v19
	v_rcp_f32_e32 v23, v23
	v_rcp_f32_e32 v24, v24
	v_rcp_f32_e32 v18, v18
	v_rcp_f32_e32 v19, v19
	v_add_f32_e32 v20, 1.0, v20
	v_add_f32_e32 v21, 1.0, v21
	v_rcp_f32_e32 v20, v20
	v_rcp_f32_e32 v21, v21
	v_fma_f32 v0, v0, s49, 0.5
	v_fma_f32 v22, v22, s49, 0.5
	v_max_f32_e32 v0, 1.0, v0
	v_max_f32_e32 v22, 1.0, v22
	v_fma_f32 v23, v23, s49, 0.5
	v_fma_f32 v24, v24, s49, 0.5
	v_fma_f32 v18, v18, s49, 0.5
	v_fma_f32 v19, v19, s49, 0.5
	v_cvt_u32_f32_e32 v0, v0
	v_cvt_u32_f32_e32 v22, v22
	v_max_f32_e32 v23, 1.0, v23
	v_max_f32_e32 v24, 1.0, v24
	v_max_f32_e32 v18, 1.0, v18
	v_max_f32_e32 v19, 1.0, v19
	v_fma_f32 v20, v20, s49, 0.5
	v_fma_f32 v21, v21, s49, 0.5
; #define GAS __attribute__((address_space(1)))
; __device__ __forceinline__ unsigned gate_pk4(const f32x4& g) { return gate_q8(g[0]) | (gate_q8(g[1]) << 8) | (gate_q8(g[2]) << 16) | (gate_q8(g[3]) << 24); }
; #define PG8_WAIT_V(n) asm volatile("s_waitcnt vmcnt(" #n ")" ::: "memory")
; #define PG8_BAR __builtin_amdgcn_s_barrier()
;     ...
;         if (!has_next) break;
; #pragma unroll
;         for (int a = 0; a < 2; ++a)
; #pragma unroll
;             for (int b = 0; b < 2; ++b)
; #pragma unroll
;                 for (int m = 0; m < 4; ++m)
; #pragma unroll
;                     for (int n = 0; n < 2; ++n) acc[a][b][m][n] = (f32x4){0.f, 0.f, 0.f, 0.f};
;         cur = nxt; cA = nA; cB = nB; ++ui;
;     }
;     PG8_WAIT_V(0);
;     if (wr == 0) PG8_BAR;
;     PG8_BAR;
;     __device__ __forceinline__ void operator()(const f32x4 (&acc)[2][2][4][2], const pg8::GUnit& u, int wr, int wc, int fr, int fq) const {
;     ...
;         GAS unsigned char* gb = (GAS unsigned char*)P + (size_t)(u.pm * 256 + (wr * 4 + wc) * 32 + fq) * (INW * 2) + (GA * 2 + u.pn * 256 + fr * 16);
; #pragma unroll
;         for (int ai = 0; ai < 2; ++ai)
; #pragma unroll
;             for (int m = 0; m < 4; ++m) { u32x4 w; unsigned wq[4];
; #pragma unroll
;                 for (int bj = 0; bj < 2; ++bj)
; #pragma unroll
;                     for (int n = 0; n < 2; ++n) { f32x4 v = acc[ai][bj][m][n];
; #pragma unroll
;                         for (int j = 0; j < 4; ++j) v[j] = __builtin_amdgcn_rcpf(1.0f + __builtin_amdgcn_exp2f(v[j] * (-LOG2E * G8_DESCALE)));
;                         wq[bj * 2 + n] = gate_pk4(v); }
;                 w.x = wq[0]; w.y = wq[1]; w.z = wq[2]; w.w = wq[3];
;                 *(GAS u32x4*)(gb + (size_t)((ai * 4 + m) * 4) * (INW * 2)) = w; }
	v_cvt_u32_f32_sdwa v23, v23 dst_sel:WORD_1 dst_unused:UNUSED_PAD src0_sel:DWORD
	v_cvt_u32_f32_sdwa v24, v24 dst_sel:BYTE_3 dst_unused:UNUSED_PAD src0_sel:DWORD
	v_cvt_u32_f32_e32 v18, v18
	v_cvt_u32_f32_e32 v19, v19
	v_max_f32_e32 v20, 1.0, v20
	v_max_f32_e32 v21, 1.0, v21
	v_cvt_u32_f32_sdwa v20, v20 dst_sel:WORD_1 dst_unused:UNUSED_PAD src0_sel:DWORD
	v_cvt_u32_f32_sdwa v21, v21 dst_sel:BYTE_3 dst_unused:UNUSED_PAD src0_sel:DWORD
	v_lshl_or_b32 v0, v22, 8, v0
	v_or3_b32 v28, v0, v23, v24
	v_lshl_or_b32 v0, v19, 8, v18
	v_or3_b32 v29, v0, v20, v21
	v_mul_f32_e32 v0, 0xba38aa3b, v14
	v_mul_f32_e32 v14, 0xba38aa3b, v15
	v_exp_f32_e32 v0, v0
	v_exp_f32_e32 v18, v14
	v_mul_f32_e32 v16, 0xba38aa3b, v16
	v_mul_f32_e32 v17, 0xba38aa3b, v17
	v_exp_f32_e32 v16, v16
	v_exp_f32_e32 v17, v17
	v_add_f32_e32 v0, 1.0, v0
	v_add_f32_e32 v18, 1.0, v18
	v_rcp_f32_e32 v0, v0
	v_rcp_f32_e32 v18, v18
	v_add_f32_e32 v16, 1.0, v16
	v_add_f32_e32 v17, 1.0, v17
	v_rcp_f32_e32 v16, v16
	v_rcp_f32_e32 v17, v17
	v_fma_f32 v0, v0, s49, 0.5
	v_fma_f32 v18, v18, s49, 0.5
	v_max_f32_e32 v0, 1.0, v0
	v_max_f32_e32 v18, 1.0, v18
	v_fma_f32 v16, v16, s49, 0.5
	v_fma_f32 v17, v17, s49, 0.5
	v_cvt_u32_f32_e32 v0, v0
	v_cvt_u32_f32_e32 v18, v18
	v_max_f32_e32 v16, 1.0, v16
	v_max_f32_e32 v17, 1.0, v17
	v_mul_f32_e32 v10, 0xba38aa3b, v10
	v_mul_f32_e32 v11, 0xba38aa3b, v11
	v_cvt_u32_f32_sdwa v16, v16 dst_sel:WORD_1 dst_unused:UNUSED_PAD src0_sel:DWORD
	v_cvt_u32_f32_sdwa v17, v17 dst_sel:BYTE_3 dst_unused:UNUSED_PAD src0_sel:DWORD
	v_exp_f32_e32 v19, v10
	v_exp_f32_e32 v11, v11
	v_lshl_or_b32 v0, v18, 8, v0
	v_or3_b32 v10, v0, v16, v17
	v_add_f32_e32 v0, 1.0, v19
	v_add_f32_e32 v11, 1.0, v11
	v_mul_f32_e32 v12, 0xba38aa3b, v12
	v_rcp_f32_e32 v0, v0
	v_rcp_f32_e32 v11, v11
	v_mul_f32_e32 v13, 0xba38aa3b, v13
	v_exp_f32_e32 v12, v12
	v_exp_f32_e32 v13, v13
	v_fma_f32 v0, v0, s49, 0.5
	v_fma_f32 v11, v11, s49, 0.5
	v_add_f32_e32 v12, 1.0, v12
	v_max_f32_e32 v0, 1.0, v0
	v_max_f32_e32 v11, 1.0, v11
	v_add_f32_e32 v13, 1.0, v13
	v_cvt_u32_f32_e32 v0, v0
	v_cvt_u32_f32_e32 v11, v11
	v_rcp_f32_e32 v12, v12
	v_rcp_f32_e32 v13, v13
	v_mul_f32_e32 v6, 0xba38aa3b, v6
	v_lshl_or_b32 v0, v11, 8, v0
	v_fma_f32 v11, v12, s49, 0.5
	v_fma_f32 v12, v13, s49, 0.5
	v_max_f32_e32 v11, 1.0, v11
	v_max_f32_e32 v12, 1.0, v12
	v_mul_f32_e32 v7, 0xba38aa3b, v7
	v_cvt_u32_f32_sdwa v11, v11 dst_sel:WORD_1 dst_unused:UNUSED_PAD src0_sel:DWORD
	v_cvt_u32_f32_sdwa v12, v12 dst_sel:BYTE_3 dst_unused:UNUSED_PAD src0_sel:DWORD
	v_exp_f32_e32 v6, v6
	v_exp_f32_e32 v7, v7
	s_lshl_b32 s39, s39, 8
	s_add_i32 s39, s40, s39
	v_or3_b32 v11, v0, v11, v12
	v_add_f32_e32 v0, 1.0, v6
	v_add_f32_e32 v6, 1.0, v7
	v_mul_f32_e32 v7, 0xba38aa3b, v8
	v_mul_f32_e32 v8, 0xba38aa3b, v9
	v_mul_f32_e32 v2, 0xba38aa3b, v2
	v_mul_f32_e32 v3, 0xba38aa3b, v3
	v_add_u32_e32 v140, s39, v140
	v_exp_f32_e32 v7, v7
	v_exp_f32_e32 v8, v8
	v_exp_f32_e32 v2, v2
	v_exp_f32_e32 v3, v3
	v_mad_i64_i32 v[140:141], s[44:45], v140, s93, v[132:133]
	v_ashrrev_i32_e32 v143, 31, v142
	v_mul_f32_e32 v4, 0xba38aa3b, v4
	v_mul_f32_e32 v5, 0xba38aa3b, v5
	v_lshl_add_u64 v[126:127], v[140:141], 0, v[142:143]
	v_exp_f32_e32 v4, v4
	v_exp_f32_e32 v5, v5
	v_add_co_u32_e32 v94, vcc, s48, v126
	v_rcp_f32_e32 v0, v0
	s_nop 0
	v_addc_co_u32_e32 v95, vcc, 0, v127, vcc
	v_rcp_f32_e32 v6, v6
	v_add_f32_e32 v7, 1.0, v7
	v_add_f32_e32 v8, 1.0, v8
	v_add_f32_e32 v2, 1.0, v2
	v_add_f32_e32 v3, 1.0, v3
	v_add_co_u32_e32 v78, vcc, s26, v126
	v_rcp_f32_e32 v7, v7
	v_rcp_f32_e32 v8, v8
	v_rcp_f32_e32 v2, v2
	v_rcp_f32_e32 v3, v3
	v_addc_co_u32_e32 v79, vcc, 0, v127, vcc
	s_mov_b32 s38, 0x90000
	v_add_f32_e32 v4, 1.0, v4
	v_add_f32_e32 v5, 1.0, v5
	v_add_co_u32_e32 v62, vcc, s38, v126
	v_rcp_f32_e32 v4, v4
	v_rcp_f32_e32 v5, v5
	v_addc_co_u32_e32 v63, vcc, 0, v127, vcc
	s_mov_b32 s38, 0xc0000
	v_fma_f32 v0, v0, s49, 0.5
	v_fma_f32 v6, v6, s49, 0.5
	v_add_co_u32_e32 v46, vcc, s38, v126
	v_max_f32_e32 v0, 1.0, v0
	v_max_f32_e32 v6, 1.0, v6
	v_fma_f32 v7, v7, s49, 0.5
	v_fma_f32 v8, v8, s49, 0.5
	v_fma_f32 v2, v2, s49, 0.5
	v_fma_f32 v3, v3, s49, 0.5
	v_addc_co_u32_e32 v47, vcc, 0, v127, vcc
	s_mov_b32 s38, 0xf0000
	v_cvt_u32_f32_e32 v0, v0
	v_cvt_u32_f32_e32 v6, v6
	v_max_f32_e32 v7, 1.0, v7
	v_max_f32_e32 v8, 1.0, v8
	v_max_f32_e32 v2, 1.0, v2
	v_max_f32_e32 v3, 1.0, v3
	v_add_co_u32_e32 v30, vcc, s38, v126
	v_cvt_u32_f32_sdwa v7, v7 dst_sel:WORD_1 dst_unused:UNUSED_PAD src0_sel:DWORD
	v_cvt_u32_f32_sdwa v8, v8 dst_sel:BYTE_3 dst_unused:UNUSED_PAD src0_sel:DWORD
	v_cvt_u32_f32_e32 v2, v2
	v_cvt_u32_f32_e32 v3, v3
	v_fma_f32 v4, v4, s49, 0.5
	v_fma_f32 v5, v5, s49, 0.5
	v_addc_co_u32_e32 v31, vcc, 0, v127, vcc
	v_max_f32_e32 v4, 1.0, v4
	v_max_f32_e32 v5, 1.0, v5
	v_add_co_u32_e32 v14, vcc, s27, v126
	v_cvt_u32_f32_sdwa v4, v4 dst_sel:WORD_1 dst_unused:UNUSED_PAD src0_sel:DWORD
	v_cvt_u32_f32_sdwa v5, v5 dst_sel:BYTE_3 dst_unused:UNUSED_PAD src0_sel:DWORD
	v_addc_co_u32_e32 v15, vcc, 0, v127, vcc
	v_lshl_or_b32 v0, v6, 8, v0
	v_or3_b32 v12, v0, v7, v8
	v_lshl_or_b32 v0, v3, 8, v2
	v_add_co_u32_e32 v2, vcc, 0x150000, v126
	v_or3_b32 v13, v0, v4, v5
	s_nop 0
	v_addc_co_u32_e32 v3, vcc, 0, v127, vcc
	s_and_b64 vcc, exec, s[4:5]
	s_mov_b32 s39, s25
	s_mov_b32 s38, s24
	s_mov_b32 s45, s37
	s_mov_b32 s44, s36
	global_store_dwordx4 v[126:127], v[122:125], off
	global_store_dwordx4 v[94:95], v[106:109], off
	global_store_dwordx4 v[78:79], v[90:93], off
	global_store_dwordx4 v[62:63], v[74:77], off
	global_store_dwordx4 v[46:47], v[58:61], off
	global_store_dwordx4 v[30:31], v[42:45], off
	global_store_dwordx4 v[14:15], v[26:29], off
	global_store_dwordx4 v[2:3], v[10:13], off
	s_cbranch_vccz .LBB0_556
	v_readlane_b32 s4, v255, 6
	s_waitcnt vmcnt(0)
	v_readlane_b32 s5, v255, 7
	s_andn2_b64 vcc, exec, s[4:5]
	s_cbranch_vccnz .LBB0_563
	s_barrier
